# attention: next iteration's first 3 K-fragment ds_reads issued in this iteration's tail (software pipeline across the back-edge), lgkmcnt recomputed
# speedup vs baseline: 1.0371x; 1.0067x over previous
; #define AT_ADV() do { kg[0] += 64 * 1024; kg[1] += 64 * 1024; vg[0] += 64; vg[1] += 64; } while (0)
; __device__ __forceinline__ void attn_unit(unsigned char* ws, const float* sub_g, LAS unsigned char* lds, int h, int qb, float negM, float lam) {
;     ...
;     const bf16_t* Qp = (const bf16_t*)(ws + WS_Q); const bf16_t* Kp = (const bf16_t*)(ws + WS_K); const bf16_t* VTp = (const bf16_t*)(ws + WS_VT);
;     bf16x8 qf[4];
;     {
;         const bf16_t* qp = Qp + (size_t)(qrow0 + r32) * 1024 + (h * 2 + map) * 64 + 8 * hi;
; #pragma unroll
;         for (int d0 = 0; d0 < 4; ++d0) qf[d0] = *(const bf16x8*)(qp + 16 * d0);
;     }
;     const bf16_t* kg[2]; const bf16_t* vg[2];
; #pragma unroll
;     for (int i = 0; i < 2; ++i) {
;         const int g = 2 * wid + i;
;         const int kr = 4 * g + (lane >> 4), kc = (lane & 15) ^ (kr & 15);
;         kg[i] = Kp + (size_t)kr * 1024 + h * 128 + kc * 8;
;         const int vr = 8 * g + (lane >> 3), vc = (lane & 7) ^ ((vr >> 1) & 7);
;         vg[i] = VTp + (size_t)(h * 128 + vr) * NTOK + vc * 8;
;     }
;     const unsigned dmaoff = (unsigned)wid * 2048u;
;     ...
;     int kad[4], vad[4];
; #pragma unroll
;     for (int d0 = 0; d0 < 4; ++d0) kad[d0] = r32 * 256 + (((map * 8 + 2 * d0 + hi) ^ (r32 & 15)) << 4);
; #pragma unroll
;     for (int j = 0; j < 4; ++j) vad[j] = AT_KBYTES + r32 * 128 + (((2 * j + hi) ^ ((r32 >> 1) & 7)) << 4);
;     ...
;     f32x16 o[4];
; #pragma unroll
;     for (int b = 0; b < 4; ++b)
; #pragma unroll
;         for (int r = 0; r < 16; ++r) o[b][r] = 0.f;
;     f32x16 negm;
; #pragma unroll
;     for (int r = 0; r < 16; ++r) negm[r] = negM;
;     float l0 = 0.f, l1 = 0.f;
;     AT_DMA(0); AT_ADV();
;     asm volatile("s_waitcnt vmcnt(0)" ::: "memory");
;     __builtin_amdgcn_s_barrier();
;     AT_DMA(AT_BUF); AT_ADV();
;     f32x16 pa, pb;
;     {
;         f32x16 s0 = negm, s1 = negm;
; #pragma unroll
;         for (int d0 = 0; d0 < 4; ++d0) { s0 = __builtin_amdgcn_mfma_f32_32x32x16_bf16(KFR(0, d0, 0), qf[d0], s0, 0, 0, 0); s1 = __builtin_amdgcn_mfma_f32_32x32x16_bf16(KFR(0, d0, 1), qf[d0], s1, 0, 0, 0); }
; #pragma unroll
;         for (int r = 0; r < 16; ++r) { pa[r] = __builtin_amdgcn_exp2f(s0[r]); pb[r] = __builtin_amdgcn_exp2f(s1[r]); }
;     }
;     asm volatile("s_waitcnt vmcnt(0) lgkmcnt(0)" ::: "memory");
;     __builtin_amdgcn_s_barrier();
.LBB0_830:
	v_readfirstlane_b32 s25, v220
	s_bfe_u32 s29, s25, 0x20006
	s_lshl_b32 s8, s20, 4
	s_and_b32 s8, s8, 0xffffff80
	s_lshl_b32 s21, s29, 5
	s_or_b32 s21, s21, s8
	s_lshr_b32 s28, s25, 8
	v_or_b32_e32 v16, s21, v148
	s_lshl_b32 s8, s20, 7
	v_ashrrev_i32_e32 v17, 31, v16
	s_and_b32 s24, s8, 0x380
	s_lshl_b32 s8, s28, 6
	v_lshlrev_b64 v[16:17], 11, v[16:17]
	s_add_i32 s8, s8, s24
	v_lshl_add_u64 v[16:17], s[4:5], 0, v[16:17]
	s_lshl_b32 s8, s8, 1
	v_lshl_add_u64 v[16:17], v[16:17], 0, s[8:9]
	v_lshlrev_b32_e32 v130, 1, v128
	v_lshl_add_u64 v[16:17], v[16:17], 0, v[130:131]
	global_load_dwordx4 v[112:115], v[16:17], off
	global_load_dwordx4 v[116:119], v[16:17], off offset:32
	global_load_dwordx4 v[120:123], v[16:17], off offset:64
	global_load_dwordx4 v[124:127], v[16:17], off offset:96
	s_lshr_b32 s33, s25, 6
	s_lshr_b32 s8, s25, 5
	s_lshl_b32 s30, s24, 1
	s_add_u32 s30, s3, s30
	s_addc_u32 s31, s18, 0
	s_lshl_b32 s34, s33, 3
	v_or_b32_e32 v130, s34, v150
	v_bitop3_b32 v18, s34, v220, v150 bitop3:0x36
	v_lshlrev_b64 v[16:17], 11, v[130:131]
	v_lshlrev_b32_e32 v18, 4, v18
	v_lshl_add_u64 v[16:17], s[30:31], 0, v[16:17]
	v_and_b32_e32 v130, 0xf0, v18
	v_lshl_add_u64 v[56:57], v[16:17], 0, v[130:131]
	v_lshl_or_b32 v16, s33, 4, v151
	v_lshrrev_b32_e32 v17, 1, v151
	v_xor_b32_e32 v20, v17, v220
	v_add_u32_e32 v18, s24, v16
	v_mov_b64_e32 v[16:17], s[6:7]
	v_mad_u64_u32 v[18:19], s[34:35], v18, s19, v[16:17]
	v_lshlrev_b32_e32 v20, 4, v20
	s_or_b32 s8, s8, 1
	v_and_b32_e32 v130, 0x70, v20
	s_lshl_b32 s34, s8, 2
	v_lshl_add_u64 v[58:59], v[18:19], 0, v[130:131]
	v_or_b32_e32 v130, s34, v150
	v_bitop3_b32 v20, s34, v220, v150 bitop3:0x36
	v_lshlrev_b64 v[18:19], 11, v[130:131]
	v_lshlrev_b32_e32 v20, 4, v20
	v_lshl_add_u64 v[18:19], s[30:31], 0, v[18:19]
	v_and_b32_e32 v130, 0xf0, v20
	v_lshl_add_u64 v[60:61], v[18:19], 0, v[130:131]
	v_lshl_or_b32 v18, s8, 3, v151
	v_lshrrev_b32_e32 v19, 1, v18
	v_add_u32_e32 v18, s24, v18
	s_lshl_b32 s8, s33, 11
	v_mad_u64_u32 v[16:17], s[30:31], v18, s19, v[16:17]
	s_add_i32 s8, s8, 0
	v_xor_b32_e32 v19, v19, v220
	s_add_i32 s31, s8, 0x4000
	s_mov_b32 m0, s8
	v_lshlrev_b32_e32 v18, 4, v19
	global_load_lds_dwordx4 v[56:57], off
	s_mov_b32 m0, s31
	v_and_b32_e32 v130, 0x70, v18
	global_load_lds_dwordx4 v[58:59], off
	s_add_i32 m0, s8, 0x400
	v_lshl_add_u64 v[62:63], v[16:17], 0, v[130:131]
	global_load_lds_dwordx4 v[60:61], off
	s_add_i32 m0, s8, 0x4400
	v_lshl_add_u64 v[16:17], v[56:57], 0, s[10:11]
	global_load_lds_dwordx4 v[62:63], off
	s_add_i32 m0, s8, 0x8000
	s_add_i32 s31, s8, 0xc000
	v_lshl_add_u64 v[20:21], v[58:59], 0, s[12:13]
	s_waitcnt vmcnt(0)
	s_barrier
	global_load_lds_dwordx4 v[16:17], off
	s_mov_b32 m0, s31
	v_lshl_add_u64 v[18:19], v[60:61], 0, s[10:11]
	global_load_lds_dwordx4 v[20:21], off
	s_add_i32 m0, s8, 0x8400
	v_lshl_add_u64 v[22:23], v[62:63], 0, s[12:13]
	global_load_lds_dwordx4 v[18:19], off
	s_add_i32 m0, s8, 0xc400
	s_lshl_b32 s30, s28, 3
	global_load_lds_dwordx4 v[22:23], off
	v_bitop3_b32 v24, s30, v153, v149 bitop3:0x36
	v_lshl_add_u32 v198, v24, 4, v154
	ds_read_b128 v[32:35], v198
	ds_read_b128 v[48:51], v198 offset:8192
	s_waitcnt lgkmcnt(0)
	v_mfma_f32_32x32x16_bf16 v[16:31], v[32:35], v[112:115], v[0:15]
	v_or_b32_e32 v64, s30, v149
	v_bitop3_b32 v32, v64, v153, 2 bitop3:0x36
	v_lshlrev_b32_e32 v65, 4, v32
	v_add_u32_e32 v52, v154, v65
	v_add_u32_e32 v200, v65, v152
	s_mov_b32 s30, 0x8000
	v_lshl_add_u64 v[140:141], v[56:57], 0, s[14:15]
	v_mfma_f32_32x32x16_bf16 v[32:47], v[48:51], v[112:115], v[0:15]
	ds_read_b128 v[48:51], v52
	ds_read_b128 v[52:55], v52 offset:8192
	v_lshl_add_u64 v[142:143], v[60:61], 0, s[14:15]
	v_lshl_add_u64 v[144:145], v[58:59], 0, s[16:17]
	v_lshl_add_u64 v[146:147], v[62:63], 0, s[16:17]
	s_mov_b32 s31, 0x18000
	s_add_i32 m0, s8, 0x10000
	s_nop 0
	global_load_lds_dwordx4 v[140:141], off
	s_add_i32 m0, s8, 0x14000
	s_nop 0
	global_load_lds_dwordx4 v[144:145], off
	s_add_i32 m0, s8, 0x10400
	s_nop 0
	global_load_lds_dwordx4 v[142:143], off
	s_add_i32 m0, s8, 0x14400
	s_nop 0
	global_load_lds_dwordx4 v[146:147], off
	v_lshl_add_u64 v[140:141], v[140:141], 0, s[10:11]
	v_lshl_add_u64 v[142:143], v[142:143], 0, s[10:11]
	v_lshl_add_u64 v[144:145], v[144:145], 0, s[12:13]
	v_lshl_add_u64 v[146:147], v[146:147], 0, s[12:13]
	s_mov_b32 s98, s3
	s_mov_b32 s99, s18
	s_mov_b64 s[100:101], s[6:7]
	v_subrev_u32_e32 v140, s3, v140
	v_subrev_u32_e32 v142, s3, v142
	v_subrev_u32_e32 v144, s6, v144
	v_subrev_u32_e32 v146, s6, v146
	v_mov_b32_e32 v216, 0
	v_mov_b32_e32 v199, 0
	s_waitcnt lgkmcnt(1)
	v_mfma_f32_32x32x16_bf16 v[16:31], v[48:51], v[116:119], v[16:31]
	v_bitop3_b32 v48, v64, v153, 4 bitop3:0x36
	v_lshlrev_b32_e32 v66, 4, v48
	v_add_u32_e32 v201, v66, v152
	s_mov_b32 s36, 0
	s_mov_b32 s33, 1
	v_mov_b32_e32 v56, v131
	v_mov_b32_e32 v57, v131
	s_waitcnt lgkmcnt(0)
	v_mfma_f32_32x32x16_bf16 v[32:47], v[52:55], v[116:119], v[32:47]
	v_add_u32_e32 v52, v154, v66
	ds_read_b128 v[48:51], v52
	ds_read_b128 v[52:55], v52 offset:8192
	v_mov_b32_e32 v58, v131
	v_mov_b32_e32 v59, v131
	v_mov_b32_e32 v60, v131
	v_mov_b32_e32 v61, v131
	v_mov_b32_e32 v62, v131
	s_waitcnt lgkmcnt(1)
	v_mfma_f32_32x32x16_bf16 v[16:31], v[48:51], v[120:123], v[16:31]
	v_bitop3_b32 v48, v64, v153, 6 bitop3:0x36
	v_lshlrev_b32_e32 v64, 4, v48
	v_add_u32_e32 v202, v64, v152
	v_mov_b32_e32 v63, v131
	v_mov_b32_e32 v65, v131
	v_mov_b32_e32 v66, v131
	v_mov_b32_e32 v67, v131
	s_waitcnt lgkmcnt(0)
	v_mfma_f32_32x32x16_bf16 v[32:47], v[52:55], v[120:123], v[32:47]
	v_add_u32_e32 v52, v154, v64
	ds_read_b128 v[48:51], v52
	ds_read_b128 v[52:55], v52 offset:8192
	s_waitcnt vmcnt(4) lgkmcnt(0)
; #define AT_ADV() do { kg[0] += 64 * 1024; kg[1] += 64 * 1024; vg[0] += 64; vg[1] += 64; } while (0)
; __device__ __forceinline__ void attn_unit(unsigned char* ws, const float* sub_g, LAS unsigned char* lds, int h, int qb, float negM, float lam) {
;     ...
;     f32x16 o[4];
; #pragma unroll
;     for (int b = 0; b < 4; ++b)
; #pragma unroll
;         for (int r = 0; r < 16; ++r) o[b][r] = 0.f;
;     f32x16 negm;
; #pragma unroll
;     for (int r = 0; r < 16; ++r) negm[r] = negM;
;     float l0 = 0.f, l1 = 0.f;
;     AT_DMA(0); AT_ADV();
;     asm volatile("s_waitcnt vmcnt(0)" ::: "memory");
;     __builtin_amdgcn_s_barrier();
;     AT_DMA(AT_BUF); AT_ADV();
;     f32x16 pa, pb;
;     {
;         f32x16 s0 = negm, s1 = negm;
; #pragma unroll
;         for (int d0 = 0; d0 < 4; ++d0) { s0 = __builtin_amdgcn_mfma_f32_32x32x16_bf16(KFR(0, d0, 0), qf[d0], s0, 0, 0, 0); s1 = __builtin_amdgcn_mfma_f32_32x32x16_bf16(KFR(0, d0, 1), qf[d0], s1, 0, 0, 0); }
; #pragma unroll
;         for (int r = 0; r < 16; ++r) { pa[r] = __builtin_amdgcn_exp2f(s0[r]); pb[r] = __builtin_amdgcn_exp2f(s1[r]); }
;     }
;     asm volatile("s_waitcnt vmcnt(0) lgkmcnt(0)" ::: "memory");
;     __builtin_amdgcn_s_barrier();
;     int bV = 0, bK = AT_BUF, bW = 2 * AT_BUF;
;     ...
;         f32x16 s0, s1;
;         bf16x8 F0 = FLOAD(0), F1 = FLOAD(1), F2;
;         SB();
;         F2 = FLOAD(2); s0 = __builtin_amdgcn_mfma_f32_32x32x16_bf16(F0, qf[0], negm, 0, 0, 0); ADD4(pa, 0); pw[0][0] = cvtpk(pa[0], pa[1]); SB();
;         F0 = FLOAD(3); s1 = __builtin_amdgcn_mfma_f32_32x32x16_bf16(F1, qf[0], negm, 0, 0, 0); ADD4(pa, 4); pw[0][1] = cvtpk(pa[2], pa[3]); SB();
;         F1 = FLOAD(4); s0 = __builtin_amdgcn_mfma_f32_32x32x16_bf16(F2, qf[1], s0, 0, 0, 0); ADD4(pa, 8); pw[0][2] = cvtpk(pa[4], pa[5]); SB();
;         F2 = FLOAD(5); s1 = __builtin_amdgcn_mfma_f32_32x32x16_bf16(F0, qf[1], s1, 0, 0, 0); ADD4(pa, 12); pw[0][3] = cvtpk(pa[6], pa[7]); SB();
;         F0 = FLOAD(6); s0 = __builtin_amdgcn_mfma_f32_32x32x16_bf16(F1, qf[2], s0, 0, 0, 0); ADD4(pb, 0); pw[1][0] = cvtpk(pa[8], pa[9]); SB();
;         F1 = FLOAD(7); s1 = __builtin_amdgcn_mfma_f32_32x32x16_bf16(F2, qf[2], s1, 0, 0, 0); ADD4(pb, 4); pw[1][1] = cvtpk(pa[10], pa[11]); SB();
;         F2 = FLOAD(8); s0 = __builtin_amdgcn_mfma_f32_32x32x16_bf16(F0, qf[3], s0, 0, 0, 0); ADD4(pb, 8); pw[1][2] = cvtpk(pa[12], pa[13]); SB();
	v_mov_b32_e32 v64, 0
	v_mov_b32_e32 v68, v131
	v_mov_b32_e32 v69, v131
	s_waitcnt lgkmcnt(1)
	v_mfma_f32_32x32x16_bf16 v[16:31], v[48:51], v[124:127], v[16:31]
	v_mov_b32_e32 v48, 0
	v_mov_b32_e32 v49, v131
	v_mov_b32_e32 v50, v131
	v_mov_b32_e32 v51, v131
	v_mov_b32_e32 v70, v131
	v_mov_b32_e32 v71, v131
	v_mov_b32_e32 v72, v131
	s_waitcnt lgkmcnt(0)
	v_mfma_f32_32x32x16_bf16 v[32:47], v[52:55], v[124:127], v[32:47]
	s_nop 2
	v_exp_f32_e32 v217, v16
	v_exp_f32_e32 v219, v17
	v_exp_f32_e32 v218, v18
	v_exp_f32_e32 v222, v19
	v_exp_f32_e32 v211, v20
	v_exp_f32_e32 v215, v21
	v_exp_f32_e32 v209, v22
	s_nop 1
	v_exp_f32_e32 v130, v32
	v_exp_f32_e32 v187, v33
	v_exp_f32_e32 v183, v34
	v_exp_f32_e32 v190, v35
	v_exp_f32_e32 v184, v36
	v_exp_f32_e32 v192, v37
	v_exp_f32_e32 v185, v38
	v_exp_f32_e32 v213, v23
	v_exp_f32_e32 v193, v39
	v_exp_f32_e32 v210, v24
	v_exp_f32_e32 v188, v40
	v_exp_f32_e32 v214, v25
	v_exp_f32_e32 v196, v41
	v_exp_f32_e32 v207, v26
	v_exp_f32_e32 v191, v42
	v_exp_f32_e32 v208, v27
	v_exp_f32_e32 v197, v43
	v_exp_f32_e32 v205, v28
	v_exp_f32_e32 v189, v44
	v_exp_f32_e32 v206, v29
	v_exp_f32_e32 v194, v45
	v_exp_f32_e32 v204, v30
	v_exp_f32_e32 v186, v46
	v_exp_f32_e32 v203, v31
	v_exp_f32_e32 v195, v47
	v_mov_b32_e32 v16, 0
	v_mov_b32_e32 v17, v131
	v_mov_b32_e32 v18, v131
	v_mov_b32_e32 v19, v131
	v_mov_b32_e32 v20, v131
	v_mov_b32_e32 v21, v131
	v_mov_b32_e32 v22, v131
	v_mov_b32_e32 v23, v131
	v_mov_b32_e32 v24, v131
	v_mov_b32_e32 v25, v131
	v_mov_b32_e32 v26, v131
	v_mov_b32_e32 v27, v131
	v_mov_b32_e32 v28, v131
	v_mov_b32_e32 v29, v131
	v_mov_b32_e32 v30, v131
	v_mov_b32_e32 v31, v131
	v_mov_b32_e32 v32, 0
	v_mov_b32_e32 v33, v131
	v_mov_b32_e32 v34, v131
	v_mov_b32_e32 v35, v131
	v_mov_b32_e32 v36, v131
	v_mov_b32_e32 v37, v131
	v_mov_b32_e32 v38, v131
	v_mov_b32_e32 v39, v131
	v_mov_b32_e32 v40, v131
	v_mov_b32_e32 v41, v131
	v_mov_b32_e32 v42, v131
	v_mov_b32_e32 v43, v131
	v_mov_b32_e32 v44, v131
	v_mov_b32_e32 v45, v131
	v_mov_b32_e32 v46, v131
	v_mov_b32_e32 v47, v131
	v_mov_b32_e32 v52, v131
	v_mov_b32_e32 v53, v131
	v_mov_b32_e32 v54, v131
	v_mov_b32_e32 v55, v131
	v_mov_b32_e32 v73, v131
	v_mov_b32_e32 v74, v131
	v_mov_b32_e32 v75, v131
	v_mov_b32_e32 v76, v131
	v_mov_b32_e32 v77, v131
	v_mov_b32_e32 v78, v131
	v_mov_b32_e32 v79, v131
	v_add_u32_e32 v247, 0x10000, v198
	v_add_u32_e32 v248, 0x10000, v200
	v_add_u32_e32 v249, 0x10000, v201
	v_add_u32_e32 v250, 0x10000, v202
	v_add_u32_e32 v251, 0x10000, v178
	v_add_u32_e32 v252, 0x10000, v179
	v_add_u32_e32 v253, 0x10000, v180
	v_add_u32_e32 v254, 0x10000, v181
	s_barrier
	ds_read_b128 v[80:83], v198 offset:32768
	ds_read_b128 v[224:227], v198 offset:40960
	ds_read_b128 v[228:231], v200 offset:32768
	s_branch .Lattn_c1
.Lattn_c1:
	v_add_f32_e32 v85, v216, v217
	v_add_f32_e32 v86, v199, v219
	s_waitcnt lgkmcnt(2)
	v_mfma_f32_32x32x16_bf16 v[96:111], v[80:83], v[112:115], v[0:15]
	v_add_f32_e32 v85, v85, v218
	v_add_f32_e32 v80, v86, v222
	v_cvt_pk_bf16_f32 v232, v217, v219
	ds_read_b128 v[236:239], v200 offset:40960
	v_add_f32_e32 v81, v85, v211
	v_add_f32_e32 v80, v80, v215
	v_cvt_pk_bf16_f32 v233, v218, v222
	v_add_f32_e32 v199, v81, v209
	v_add_f32_e32 v223, v80, v213
	s_waitcnt lgkmcnt(2)
	v_mfma_f32_32x32x16_bf16 v[80:95], v[224:227], v[112:115], v[0:15]
	ds_read_b128 v[216:219], v201 offset:32768
	v_add_f32_e32 v199, v199, v210
	v_add_f32_e32 v223, v223, v214
	s_waitcnt lgkmcnt(2)
	v_mfma_f32_32x32x16_bf16 v[96:111], v[228:231], v[116:119], v[96:111]
	v_add_f32_e32 v199, v199, v207
	v_add_f32_e32 v226, v223, v208
	v_cvt_pk_bf16_f32 v234, v211, v215
	ds_read_b128 v[222:225], v201 offset:40960
	v_add_f32_e32 v199, v199, v205
	v_add_f32_e32 v211, v226, v206
	v_cvt_pk_bf16_f32 v235, v209, v213
	v_add_f32_e32 v199, v199, v204
	v_add_f32_e32 v211, v211, v203
	s_waitcnt lgkmcnt(2)
	v_mfma_f32_32x32x16_bf16 v[80:95], v[236:239], v[116:119], v[80:95]
	ds_read_b128 v[226:229], v202 offset:32768
	v_add_f32_e32 v199, v199, v130
	v_add_f32_e32 v211, v211, v187
	s_waitcnt lgkmcnt(2)
	v_mfma_f32_32x32x16_bf16 v[96:111], v[216:219], v[120:123], v[96:111]
	v_add_f32_e32 v199, v199, v183
	v_add_f32_e32 v211, v211, v190
	v_cvt_pk_bf16_f32 v236, v210, v214
	ds_read_b128 v[240:243], v202 offset:40960
	v_add_f32_e32 v199, v199, v184
	v_add_f32_e32 v209, v211, v192
	v_cvt_pk_bf16_f32 v237, v207, v208
	v_add_f32_e32 v199, v199, v185
	v_add_f32_e32 v213, v209, v193
	s_waitcnt lgkmcnt(2)
	v_mfma_f32_32x32x16_bf16 v[80:95], v[222:225], v[120:123], v[80:95]
	ds_read_b128 v[208:211], v178 offset:16384
	v_add_f32_e32 v199, v199, v188
	v_add_f32_e32 v207, v213, v196
	s_waitcnt lgkmcnt(2)
	v_mfma_f32_32x32x16_bf16 v[96:111], v[226:229], v[124:127], v[96:111]
	v_add_f32_e32 v199, v199, v191
	v_add_f32_e32 v207, v207, v197
	v_cvt_pk_bf16_f32 v238, v205, v206
	ds_read_b128 v[224:227], v178 offset:20480
	v_add_f32_e32 v199, v199, v189
	v_add_f32_e32 v205, v207, v194
	v_cvt_pk_bf16_f32 v239, v204, v203
	v_add_f32_e32 v216, v199, v186
	v_add_f32_e32 v199, v205, v195
	s_waitcnt lgkmcnt(2)
	v_mfma_f32_32x32x16_bf16 v[80:95], v[240:243], v[124:127], v[80:95]
	s_waitcnt vmcnt(0)
	s_barrier
; __device__ __forceinline__ void attn_unit(unsigned char* ws, const float* sub_g, LAS unsigned char* lds, int h, int qb, float negM, float lam) {
;     ...
;         F1 = FLOAD(10); o[0] = __builtin_amdgcn_mfma_f32_32x32x16_bf16(F2, __builtin_bit_cast(bf16x8, pw[0]), o[0], 0, 0, 0); pw[2][0] = cvtpk(pb[0], pb[1]); EXP2(s0, pa, 0); SB();
;         F2 = FLOAD(11); o[1] = __builtin_amdgcn_mfma_f32_32x32x16_bf16(F0, __builtin_bit_cast(bf16x8, pw[0]), o[1], 0, 0, 0); pw[2][1] = cvtpk(pb[2], pb[3]); EXP2(s0, pa, 2); SB();
;         F0 = FLOAD(12); o[2] = __builtin_amdgcn_mfma_f32_32x32x16_bf16(F1, __builtin_bit_cast(bf16x8, pw[0]), o[2], 0, 0, 0); pw[2][2] = cvtpk(pb[4], pb[5]); EXP2(s0, pa, 4); SB();
;         F1 = FLOAD(13); o[3] = __builtin_amdgcn_mfma_f32_32x32x16_bf16(F2, __builtin_bit_cast(bf16x8, pw[0]), o[3], 0, 0, 0); pw[2][3] = cvtpk(pb[6], pb[7]); EXP2(s0, pa, 6); SB();
;         F2 = FLOAD(14); o[0] = __builtin_amdgcn_mfma_f32_32x32x16_bf16(F0, __builtin_bit_cast(bf16x8, pw[1]), o[0], 0, 0, 0); pw[3][0] = cvtpk(pb[8], pb[9]); EXP2(s0, pa, 8); SB();
;         F0 = FLOAD(15); o[1] = __builtin_amdgcn_mfma_f32_32x32x16_bf16(F1, __builtin_bit_cast(bf16x8, pw[1]), o[1], 0, 0, 0); pw[3][1] = cvtpk(pb[10], pb[11]); EXP2(s0, pa, 10); SB();
;         F1 = FLOAD(16); o[2] = __builtin_amdgcn_mfma_f32_32x32x16_bf16(F2, __builtin_bit_cast(bf16x8, pw[1]), o[2], 0, 0, 0); pw[3][2] = cvtpk(pb[12], pb[13]); EXP2(s0, pa, 12); SB();
;         F2 = FLOAD(17); o[3] = __builtin_amdgcn_mfma_f32_32x32x16_bf16(F0, __builtin_bit_cast(bf16x8, pw[1]), o[3], 0, 0, 0); pw[3][3] = cvtpk(pb[14], pb[15]); EXP2(s0, pa, 14); SB();
;         F0 = FLOAD(18); o[0] = __builtin_amdgcn_mfma_f32_32x32x16_bf16(F1, __builtin_bit_cast(bf16x8, pw[2]), o[0], 0, 0, 0); EXP2(s1, pb, 0); SB();
;         F1 = FLOAD(19); o[1] = __builtin_amdgcn_mfma_f32_32x32x16_bf16(F2, __builtin_bit_cast(bf16x8, pw[2]), o[1], 0, 0, 0); EXP2(s1, pb, 2); SB();
;         F2 = FLOAD(20); o[2] = __builtin_amdgcn_mfma_f32_32x32x16_bf16(F0, __builtin_bit_cast(bf16x8, pw[2]), o[2], 0, 0, 0); EXP2(s1, pb, 4); SB();
;         F0 = FLOAD(21); o[3] = __builtin_amdgcn_mfma_f32_32x32x16_bf16(F1, __builtin_bit_cast(bf16x8, pw[2]), o[3], 0, 0, 0); EXP2(s1, pb, 6); SB();
;         F1 = FLOAD(22); o[0] = __builtin_amdgcn_mfma_f32_32x32x16_bf16(F2, __builtin_bit_cast(bf16x8, pw[3]), o[0], 0, 0, 0); EXP2(s1, pb, 8); SB();
	s_waitcnt lgkmcnt(1)
	v_mfma_f32_32x32x16_bf16 v[64:79], v[208:211], v[232:235], v[64:79]
	s_add_i32 m0, s8, 0x18000
	ds_read_b128 v[204:207], v178 offset:24576
	global_load_lds_dwordx4 v140, s[98:99]
	v_exp_f32_e32 v217, v96
	v_exp_f32_e32 v219, v97
	v_cvt_pk_bf16_f32 v228, v130, v187
	s_waitcnt lgkmcnt(1)
	v_mfma_f32_32x32x16_bf16 v[48:63], v[224:227], v[232:235], v[48:63]
	ds_read_b128 v[240:243], v178 offset:28672
	v_exp_f32_e32 v218, v98
	v_exp_f32_e32 v222, v99
	v_cvt_pk_bf16_f32 v229, v183, v190
	s_waitcnt lgkmcnt(1)
	v_mfma_f32_32x32x16_bf16 v[32:47], v[204:207], v[232:235], v[32:47]
	s_add_i32 m0, m0, 0x4000
	ds_read_b128 v[96:99], v179 offset:16384
	global_load_lds_dwordx4 v144, s[100:101]
	v_exp_f32_e32 v211, v100
	v_exp_f32_e32 v215, v101
	v_cvt_pk_bf16_f32 v230, v184, v192
	s_waitcnt lgkmcnt(1)
	v_mfma_f32_32x32x16_bf16 v[16:31], v[240:243], v[232:235], v[16:31]
	ds_read_b128 v[224:227], v179 offset:20480
	v_exp_f32_e32 v209, v102
	v_exp_f32_e32 v213, v103
	v_cvt_pk_bf16_f32 v231, v185, v193
	s_waitcnt lgkmcnt(1)
	v_mfma_f32_32x32x16_bf16 v[64:79], v[96:99], v[236:239], v[64:79]
	s_add_i32 m0, m0, 0xffffc400
	ds_read_b128 v[100:103], v179 offset:24576
	global_load_lds_dwordx4 v142, s[98:99]
	v_exp_f32_e32 v210, v104
	v_exp_f32_e32 v214, v105
	v_cvt_pk_bf16_f32 v232, v188, v196
	s_waitcnt lgkmcnt(1)
	v_mfma_f32_32x32x16_bf16 v[48:63], v[224:227], v[236:239], v[48:63]
	ds_read_b128 v[96:99], v179 offset:28672
	v_exp_f32_e32 v207, v106
	v_exp_f32_e32 v208, v107
	v_cvt_pk_bf16_f32 v233, v191, v197
	s_waitcnt lgkmcnt(1)
	v_mfma_f32_32x32x16_bf16 v[32:47], v[100:103], v[236:239], v[32:47]
	s_add_i32 m0, m0, 0x4000
	ds_read_b128 v[104:107], v180 offset:16384
	global_load_lds_dwordx4 v146, s[100:101]
	s_add_u32 s98, s98, 0x20000
	s_addc_u32 s99, s99, 0
	s_add_u32 s100, s100, 0x80
	s_addc_u32 s101, s101, 0
	v_exp_f32_e32 v205, v108
	v_exp_f32_e32 v206, v109
	v_cvt_pk_bf16_f32 v234, v189, v194
	s_waitcnt lgkmcnt(1)
	v_mfma_f32_32x32x16_bf16 v[16:31], v[96:99], v[236:239], v[16:31]
	ds_read_b128 v[100:103], v180 offset:20480
	v_exp_f32_e32 v204, v110
	v_exp_f32_e32 v203, v111
	v_cvt_pk_bf16_f32 v235, v186, v195
	s_waitcnt lgkmcnt(1)
	v_mfma_f32_32x32x16_bf16 v[64:79], v[104:107], v[228:231], v[64:79]
	ds_read_b128 v[96:99], v180 offset:24576
	v_exp_f32_e32 v130, v80
	v_exp_f32_e32 v187, v81
	s_waitcnt lgkmcnt(1)
	v_mfma_f32_32x32x16_bf16 v[48:63], v[100:103], v[228:231], v[48:63]
	ds_read_b128 v[104:107], v180 offset:28672
	v_exp_f32_e32 v183, v82
	v_exp_f32_e32 v190, v83
	s_waitcnt lgkmcnt(1)
	v_mfma_f32_32x32x16_bf16 v[32:47], v[96:99], v[228:231], v[32:47]
	ds_read_b128 v[80:83], v181 offset:16384
	v_exp_f32_e32 v184, v84
	v_exp_f32_e32 v192, v85
	s_waitcnt lgkmcnt(1)
	v_mfma_f32_32x32x16_bf16 v[16:31], v[104:107], v[228:231], v[16:31]
	ds_read_b128 v[96:99], v181 offset:20480
	v_exp_f32_e32 v185, v86
	v_exp_f32_e32 v193, v87
	s_waitcnt lgkmcnt(1)
	v_mfma_f32_32x32x16_bf16 v[64:79], v[80:83], v[232:235], v[64:79]
	ds_read_b128 v[84:87], v181 offset:24576
	ds_read_b128 v[80:83], v247
	v_exp_f32_e32 v188, v88
	v_exp_f32_e32 v196, v89
	s_waitcnt lgkmcnt(2)
	v_mfma_f32_32x32x16_bf16 v[48:63], v[96:99], v[232:235], v[48:63]
	ds_read_b128 v[100:103], v181 offset:28672
	ds_read_b128 v[224:227], v247 offset:8192
	v_exp_f32_e32 v191, v90
	v_exp_f32_e32 v197, v91
	s_waitcnt lgkmcnt(3)
	v_mfma_f32_32x32x16_bf16 v[32:47], v[84:87], v[232:235], v[32:47]
	ds_read_b128 v[228:231], v248
	v_exp_f32_e32 v189, v92
	v_exp_f32_e32 v194, v93
	s_waitcnt lgkmcnt(2)
	v_mfma_f32_32x32x16_bf16 v[16:31], v[100:103], v[232:235], v[16:31]
	v_exp_f32_e32 v186, v94
	v_exp_f32_e32 v195, v95
	s_add_i32 s33, s33, 1
.Lattn_c2:
	v_add_f32_e32 v85, v216, v217
	v_add_f32_e32 v86, v199, v219
	s_waitcnt lgkmcnt(2)
	v_mfma_f32_32x32x16_bf16 v[96:111], v[80:83], v[112:115], v[0:15]
	v_add_f32_e32 v85, v85, v218
	v_add_f32_e32 v80, v86, v222
	v_cvt_pk_bf16_f32 v232, v217, v219
	ds_read_b128 v[236:239], v248 offset:8192
	v_add_f32_e32 v81, v85, v211
	v_add_f32_e32 v80, v80, v215
	v_cvt_pk_bf16_f32 v233, v218, v222
	v_add_f32_e32 v199, v81, v209
	v_add_f32_e32 v223, v80, v213
	s_waitcnt lgkmcnt(2)
	v_mfma_f32_32x32x16_bf16 v[80:95], v[224:227], v[112:115], v[0:15]
	ds_read_b128 v[216:219], v249
	v_add_f32_e32 v199, v199, v210
	v_add_f32_e32 v223, v223, v214
	s_waitcnt lgkmcnt(2)
	v_mfma_f32_32x32x16_bf16 v[96:111], v[228:231], v[116:119], v[96:111]
	v_add_f32_e32 v199, v199, v207
	v_add_f32_e32 v226, v223, v208
	v_cvt_pk_bf16_f32 v234, v211, v215
	ds_read_b128 v[222:225], v249 offset:8192
	v_add_f32_e32 v199, v199, v205
	v_add_f32_e32 v211, v226, v206
	v_cvt_pk_bf16_f32 v235, v209, v213
	v_add_f32_e32 v199, v199, v204
	v_add_f32_e32 v211, v211, v203
	s_waitcnt lgkmcnt(2)
	v_mfma_f32_32x32x16_bf16 v[80:95], v[236:239], v[116:119], v[80:95]
	ds_read_b128 v[226:229], v250
	v_add_f32_e32 v199, v199, v130
	v_add_f32_e32 v211, v211, v187
	s_waitcnt lgkmcnt(2)
	v_mfma_f32_32x32x16_bf16 v[96:111], v[216:219], v[120:123], v[96:111]
	v_add_f32_e32 v199, v199, v183
	v_add_f32_e32 v211, v211, v190
	v_cvt_pk_bf16_f32 v236, v210, v214
	ds_read_b128 v[240:243], v250 offset:8192
	v_add_f32_e32 v199, v199, v184
	v_add_f32_e32 v209, v211, v192
	v_cvt_pk_bf16_f32 v237, v207, v208
	v_add_f32_e32 v199, v199, v185
	v_add_f32_e32 v213, v209, v193
	s_waitcnt lgkmcnt(2)
	v_mfma_f32_32x32x16_bf16 v[80:95], v[222:225], v[120:123], v[80:95]
	ds_read_b128 v[208:211], v178 offset:49152
	v_add_f32_e32 v199, v199, v188
	v_add_f32_e32 v207, v213, v196
	s_waitcnt lgkmcnt(2)
	v_mfma_f32_32x32x16_bf16 v[96:111], v[226:229], v[124:127], v[96:111]
	v_add_f32_e32 v199, v199, v191
	v_add_f32_e32 v207, v207, v197
	v_cvt_pk_bf16_f32 v238, v205, v206
	ds_read_b128 v[224:227], v178 offset:53248
	v_add_f32_e32 v199, v199, v189
	v_add_f32_e32 v205, v207, v194
	v_cvt_pk_bf16_f32 v239, v204, v203
	v_add_f32_e32 v216, v199, v186
	v_add_f32_e32 v199, v205, v195
	s_waitcnt lgkmcnt(2)
	v_mfma_f32_32x32x16_bf16 v[80:95], v[240:243], v[124:127], v[80:95]
	s_waitcnt vmcnt(0)
	s_barrier
; __device__ __forceinline__ void attn_unit(unsigned char* ws, const float* sub_g, LAS unsigned char* lds, int h, int qb, float negM, float lam) {
;     ...
;         F1 = FLOAD(10); o[0] = __builtin_amdgcn_mfma_f32_32x32x16_bf16(F2, __builtin_bit_cast(bf16x8, pw[0]), o[0], 0, 0, 0); pw[2][0] = cvtpk(pb[0], pb[1]); EXP2(s0, pa, 0); SB();
;         F2 = FLOAD(11); o[1] = __builtin_amdgcn_mfma_f32_32x32x16_bf16(F0, __builtin_bit_cast(bf16x8, pw[0]), o[1], 0, 0, 0); pw[2][1] = cvtpk(pb[2], pb[3]); EXP2(s0, pa, 2); SB();
;         F0 = FLOAD(12); o[2] = __builtin_amdgcn_mfma_f32_32x32x16_bf16(F1, __builtin_bit_cast(bf16x8, pw[0]), o[2], 0, 0, 0); pw[2][2] = cvtpk(pb[4], pb[5]); EXP2(s0, pa, 4); SB();
;         F1 = FLOAD(13); o[3] = __builtin_amdgcn_mfma_f32_32x32x16_bf16(F2, __builtin_bit_cast(bf16x8, pw[0]), o[3], 0, 0, 0); pw[2][3] = cvtpk(pb[6], pb[7]); EXP2(s0, pa, 6); SB();
;         F2 = FLOAD(14); o[0] = __builtin_amdgcn_mfma_f32_32x32x16_bf16(F0, __builtin_bit_cast(bf16x8, pw[1]), o[0], 0, 0, 0); pw[3][0] = cvtpk(pb[8], pb[9]); EXP2(s0, pa, 8); SB();
;         F0 = FLOAD(15); o[1] = __builtin_amdgcn_mfma_f32_32x32x16_bf16(F1, __builtin_bit_cast(bf16x8, pw[1]), o[1], 0, 0, 0); pw[3][1] = cvtpk(pb[10], pb[11]); EXP2(s0, pa, 10); SB();
;         F1 = FLOAD(16); o[2] = __builtin_amdgcn_mfma_f32_32x32x16_bf16(F2, __builtin_bit_cast(bf16x8, pw[1]), o[2], 0, 0, 0); pw[3][2] = cvtpk(pb[12], pb[13]); EXP2(s0, pa, 12); SB();
;         F2 = FLOAD(17); o[3] = __builtin_amdgcn_mfma_f32_32x32x16_bf16(F0, __builtin_bit_cast(bf16x8, pw[1]), o[3], 0, 0, 0); pw[3][3] = cvtpk(pb[14], pb[15]); EXP2(s0, pa, 14); SB();
;         F0 = FLOAD(18); o[0] = __builtin_amdgcn_mfma_f32_32x32x16_bf16(F1, __builtin_bit_cast(bf16x8, pw[2]), o[0], 0, 0, 0); EXP2(s1, pb, 0); SB();
;         F1 = FLOAD(19); o[1] = __builtin_amdgcn_mfma_f32_32x32x16_bf16(F2, __builtin_bit_cast(bf16x8, pw[2]), o[1], 0, 0, 0); EXP2(s1, pb, 2); SB();
;         F2 = FLOAD(20); o[2] = __builtin_amdgcn_mfma_f32_32x32x16_bf16(F0, __builtin_bit_cast(bf16x8, pw[2]), o[2], 0, 0, 0); EXP2(s1, pb, 4); SB();
;         F0 = FLOAD(21); o[3] = __builtin_amdgcn_mfma_f32_32x32x16_bf16(F1, __builtin_bit_cast(bf16x8, pw[2]), o[3], 0, 0, 0); EXP2(s1, pb, 6); SB();
;         F1 = FLOAD(22); o[0] = __builtin_amdgcn_mfma_f32_32x32x16_bf16(F2, __builtin_bit_cast(bf16x8, pw[3]), o[0], 0, 0, 0); EXP2(s1, pb, 8); SB();
	s_waitcnt lgkmcnt(1)
	v_mfma_f32_32x32x16_bf16 v[64:79], v[208:211], v[232:235], v[64:79]
	s_add_i32 m0, s8, 0x0
	ds_read_b128 v[204:207], v178 offset:57344
	global_load_lds_dwordx4 v140, s[98:99]
	v_exp_f32_e32 v217, v96
	v_exp_f32_e32 v219, v97
	v_cvt_pk_bf16_f32 v228, v130, v187
	s_waitcnt lgkmcnt(1)
	v_mfma_f32_32x32x16_bf16 v[48:63], v[224:227], v[232:235], v[48:63]
	ds_read_b128 v[240:243], v178 offset:61440
	v_exp_f32_e32 v218, v98
	v_exp_f32_e32 v222, v99
	v_cvt_pk_bf16_f32 v229, v183, v190
	s_waitcnt lgkmcnt(1)
	v_mfma_f32_32x32x16_bf16 v[32:47], v[204:207], v[232:235], v[32:47]
	s_add_i32 m0, m0, 0x4000
	ds_read_b128 v[96:99], v179 offset:49152
	global_load_lds_dwordx4 v144, s[100:101]
	v_exp_f32_e32 v211, v100
	v_exp_f32_e32 v215, v101
	v_cvt_pk_bf16_f32 v230, v184, v192
	s_waitcnt lgkmcnt(1)
	v_mfma_f32_32x32x16_bf16 v[16:31], v[240:243], v[232:235], v[16:31]
	ds_read_b128 v[224:227], v179 offset:53248
	v_exp_f32_e32 v209, v102
	v_exp_f32_e32 v213, v103
	v_cvt_pk_bf16_f32 v231, v185, v193
	s_waitcnt lgkmcnt(1)
	v_mfma_f32_32x32x16_bf16 v[64:79], v[96:99], v[236:239], v[64:79]
	s_add_i32 m0, m0, 0xffffc400
	ds_read_b128 v[100:103], v179 offset:57344
	global_load_lds_dwordx4 v142, s[98:99]
	v_exp_f32_e32 v210, v104
	v_exp_f32_e32 v214, v105
	v_cvt_pk_bf16_f32 v232, v188, v196
	s_waitcnt lgkmcnt(1)
	v_mfma_f32_32x32x16_bf16 v[48:63], v[224:227], v[236:239], v[48:63]
	ds_read_b128 v[96:99], v179 offset:61440
	v_exp_f32_e32 v207, v106
	v_exp_f32_e32 v208, v107
	v_cvt_pk_bf16_f32 v233, v191, v197
	s_waitcnt lgkmcnt(1)
	v_mfma_f32_32x32x16_bf16 v[32:47], v[100:103], v[236:239], v[32:47]
	s_add_i32 m0, m0, 0x4000
	ds_read_b128 v[104:107], v180 offset:49152
	global_load_lds_dwordx4 v146, s[100:101]
	s_add_u32 s98, s98, 0x20000
	s_addc_u32 s99, s99, 0
	s_add_u32 s100, s100, 0x80
	s_addc_u32 s101, s101, 0
	v_exp_f32_e32 v205, v108
	v_exp_f32_e32 v206, v109
	v_cvt_pk_bf16_f32 v234, v189, v194
	s_waitcnt lgkmcnt(1)
	v_mfma_f32_32x32x16_bf16 v[16:31], v[96:99], v[236:239], v[16:31]
	ds_read_b128 v[100:103], v180 offset:53248
	v_exp_f32_e32 v204, v110
	v_exp_f32_e32 v203, v111
	v_cvt_pk_bf16_f32 v235, v186, v195
	s_waitcnt lgkmcnt(1)
	v_mfma_f32_32x32x16_bf16 v[64:79], v[104:107], v[228:231], v[64:79]
	ds_read_b128 v[96:99], v180 offset:57344
	v_exp_f32_e32 v130, v80
	v_exp_f32_e32 v187, v81
	s_waitcnt lgkmcnt(1)
	v_mfma_f32_32x32x16_bf16 v[48:63], v[100:103], v[228:231], v[48:63]
	ds_read_b128 v[104:107], v180 offset:61440
	v_exp_f32_e32 v183, v82
	v_exp_f32_e32 v190, v83
	s_waitcnt lgkmcnt(1)
	v_mfma_f32_32x32x16_bf16 v[32:47], v[96:99], v[228:231], v[32:47]
	ds_read_b128 v[80:83], v181 offset:49152
	v_exp_f32_e32 v184, v84
	v_exp_f32_e32 v192, v85
	s_waitcnt lgkmcnt(1)
	v_mfma_f32_32x32x16_bf16 v[16:31], v[104:107], v[228:231], v[16:31]
	ds_read_b128 v[96:99], v181 offset:53248
	v_exp_f32_e32 v185, v86
	v_exp_f32_e32 v193, v87
	s_waitcnt lgkmcnt(1)
	v_mfma_f32_32x32x16_bf16 v[64:79], v[80:83], v[232:235], v[64:79]
	ds_read_b128 v[84:87], v181 offset:57344
	ds_read_b128 v[80:83], v247 offset:32768
	v_exp_f32_e32 v188, v88
	v_exp_f32_e32 v196, v89
	s_waitcnt lgkmcnt(2)
	v_mfma_f32_32x32x16_bf16 v[48:63], v[96:99], v[232:235], v[48:63]
	ds_read_b128 v[100:103], v181 offset:61440
	ds_read_b128 v[224:227], v247 offset:40960
	v_exp_f32_e32 v191, v90
	v_exp_f32_e32 v197, v91
	s_waitcnt lgkmcnt(3)
	v_mfma_f32_32x32x16_bf16 v[32:47], v[84:87], v[232:235], v[32:47]
	ds_read_b128 v[228:231], v248 offset:32768
	v_exp_f32_e32 v189, v92
	v_exp_f32_e32 v194, v93
	s_waitcnt lgkmcnt(2)
	v_mfma_f32_32x32x16_bf16 v[16:31], v[100:103], v[232:235], v[16:31]
	v_exp_f32_e32 v186, v94
	v_exp_f32_e32 v195, v95
	s_add_i32 s33, s33, 1
.Lattn_c3:
	v_add_f32_e32 v85, v216, v217
	v_add_f32_e32 v86, v199, v219
	s_waitcnt lgkmcnt(2)
	v_mfma_f32_32x32x16_bf16 v[96:111], v[80:83], v[112:115], v[0:15]
	v_add_f32_e32 v85, v85, v218
	v_add_f32_e32 v80, v86, v222
	v_cvt_pk_bf16_f32 v232, v217, v219
	ds_read_b128 v[236:239], v248 offset:40960
	v_add_f32_e32 v81, v85, v211
	v_add_f32_e32 v80, v80, v215
	v_cvt_pk_bf16_f32 v233, v218, v222
	v_add_f32_e32 v199, v81, v209
	v_add_f32_e32 v223, v80, v213
	s_waitcnt lgkmcnt(2)
	v_mfma_f32_32x32x16_bf16 v[80:95], v[224:227], v[112:115], v[0:15]
	ds_read_b128 v[216:219], v249 offset:32768
	v_add_f32_e32 v199, v199, v210
	v_add_f32_e32 v223, v223, v214
	s_waitcnt lgkmcnt(2)
	v_mfma_f32_32x32x16_bf16 v[96:111], v[228:231], v[116:119], v[96:111]
	v_add_f32_e32 v199, v199, v207
	v_add_f32_e32 v226, v223, v208
	v_cvt_pk_bf16_f32 v234, v211, v215
	ds_read_b128 v[222:225], v249 offset:40960
	v_add_f32_e32 v199, v199, v205
	v_add_f32_e32 v211, v226, v206
	v_cvt_pk_bf16_f32 v235, v209, v213
	v_add_f32_e32 v199, v199, v204
	v_add_f32_e32 v211, v211, v203
	s_waitcnt lgkmcnt(2)
	v_mfma_f32_32x32x16_bf16 v[80:95], v[236:239], v[116:119], v[80:95]
	ds_read_b128 v[226:229], v250 offset:32768
	v_add_f32_e32 v199, v199, v130
	v_add_f32_e32 v211, v211, v187
	s_waitcnt lgkmcnt(2)
	v_mfma_f32_32x32x16_bf16 v[96:111], v[216:219], v[120:123], v[96:111]
	v_add_f32_e32 v199, v199, v183
	v_add_f32_e32 v211, v211, v190
	v_cvt_pk_bf16_f32 v236, v210, v214
	ds_read_b128 v[240:243], v250 offset:40960
	v_add_f32_e32 v199, v199, v184
	v_add_f32_e32 v209, v211, v192
	v_cvt_pk_bf16_f32 v237, v207, v208
	v_add_f32_e32 v199, v199, v185
	v_add_f32_e32 v213, v209, v193
	s_waitcnt lgkmcnt(2)
	v_mfma_f32_32x32x16_bf16 v[80:95], v[222:225], v[120:123], v[80:95]
	ds_read_b128 v[208:211], v251 offset:16384
	v_add_f32_e32 v199, v199, v188
	v_add_f32_e32 v207, v213, v196
	s_waitcnt lgkmcnt(2)
	v_mfma_f32_32x32x16_bf16 v[96:111], v[226:229], v[124:127], v[96:111]
	v_add_f32_e32 v199, v199, v191
	v_add_f32_e32 v207, v207, v197
	v_cvt_pk_bf16_f32 v238, v205, v206
	ds_read_b128 v[224:227], v251 offset:20480
	v_add_f32_e32 v199, v199, v189
	v_add_f32_e32 v205, v207, v194
	v_cvt_pk_bf16_f32 v239, v204, v203
	v_add_f32_e32 v216, v199, v186
	v_add_f32_e32 v199, v205, v195
	s_waitcnt lgkmcnt(2)
	v_mfma_f32_32x32x16_bf16 v[80:95], v[240:243], v[124:127], v[80:95]
	s_waitcnt vmcnt(0)
	s_barrier
; __device__ __forceinline__ void attn_unit(unsigned char* ws, const float* sub_g, LAS unsigned char* lds, int h, int qb, float negM, float lam) {
;     ...
;         F1 = FLOAD(10); o[0] = __builtin_amdgcn_mfma_f32_32x32x16_bf16(F2, __builtin_bit_cast(bf16x8, pw[0]), o[0], 0, 0, 0); pw[2][0] = cvtpk(pb[0], pb[1]); EXP2(s0, pa, 0); SB();
;         F2 = FLOAD(11); o[1] = __builtin_amdgcn_mfma_f32_32x32x16_bf16(F0, __builtin_bit_cast(bf16x8, pw[0]), o[1], 0, 0, 0); pw[2][1] = cvtpk(pb[2], pb[3]); EXP2(s0, pa, 2); SB();
;         F0 = FLOAD(12); o[2] = __builtin_amdgcn_mfma_f32_32x32x16_bf16(F1, __builtin_bit_cast(bf16x8, pw[0]), o[2], 0, 0, 0); pw[2][2] = cvtpk(pb[4], pb[5]); EXP2(s0, pa, 4); SB();
;         F1 = FLOAD(13); o[3] = __builtin_amdgcn_mfma_f32_32x32x16_bf16(F2, __builtin_bit_cast(bf16x8, pw[0]), o[3], 0, 0, 0); pw[2][3] = cvtpk(pb[6], pb[7]); EXP2(s0, pa, 6); SB();
;         F2 = FLOAD(14); o[0] = __builtin_amdgcn_mfma_f32_32x32x16_bf16(F0, __builtin_bit_cast(bf16x8, pw[1]), o[0], 0, 0, 0); pw[3][0] = cvtpk(pb[8], pb[9]); EXP2(s0, pa, 8); SB();
;         F0 = FLOAD(15); o[1] = __builtin_amdgcn_mfma_f32_32x32x16_bf16(F1, __builtin_bit_cast(bf16x8, pw[1]), o[1], 0, 0, 0); pw[3][1] = cvtpk(pb[10], pb[11]); EXP2(s0, pa, 10); SB();
;         F1 = FLOAD(16); o[2] = __builtin_amdgcn_mfma_f32_32x32x16_bf16(F2, __builtin_bit_cast(bf16x8, pw[1]), o[2], 0, 0, 0); pw[3][2] = cvtpk(pb[12], pb[13]); EXP2(s0, pa, 12); SB();
;         F2 = FLOAD(17); o[3] = __builtin_amdgcn_mfma_f32_32x32x16_bf16(F0, __builtin_bit_cast(bf16x8, pw[1]), o[3], 0, 0, 0); pw[3][3] = cvtpk(pb[14], pb[15]); EXP2(s0, pa, 14); SB();
;         F0 = FLOAD(18); o[0] = __builtin_amdgcn_mfma_f32_32x32x16_bf16(F1, __builtin_bit_cast(bf16x8, pw[2]), o[0], 0, 0, 0); EXP2(s1, pb, 0); SB();
;         F1 = FLOAD(19); o[1] = __builtin_amdgcn_mfma_f32_32x32x16_bf16(F2, __builtin_bit_cast(bf16x8, pw[2]), o[1], 0, 0, 0); EXP2(s1, pb, 2); SB();
;         F2 = FLOAD(20); o[2] = __builtin_amdgcn_mfma_f32_32x32x16_bf16(F0, __builtin_bit_cast(bf16x8, pw[2]), o[2], 0, 0, 0); EXP2(s1, pb, 4); SB();
;         F0 = FLOAD(21); o[3] = __builtin_amdgcn_mfma_f32_32x32x16_bf16(F1, __builtin_bit_cast(bf16x8, pw[2]), o[3], 0, 0, 0); EXP2(s1, pb, 6); SB();
;         F1 = FLOAD(22); o[0] = __builtin_amdgcn_mfma_f32_32x32x16_bf16(F2, __builtin_bit_cast(bf16x8, pw[3]), o[0], 0, 0, 0); EXP2(s1, pb, 8); SB();
	s_waitcnt lgkmcnt(1)
	v_mfma_f32_32x32x16_bf16 v[64:79], v[208:211], v[232:235], v[64:79]
	s_add_i32 m0, s8, 0x8000
	ds_read_b128 v[204:207], v251 offset:24576
	global_load_lds_dwordx4 v140, s[98:99]
	v_exp_f32_e32 v217, v96
	v_exp_f32_e32 v219, v97
	v_cvt_pk_bf16_f32 v228, v130, v187
	s_waitcnt lgkmcnt(1)
	v_mfma_f32_32x32x16_bf16 v[48:63], v[224:227], v[232:235], v[48:63]
	ds_read_b128 v[240:243], v251 offset:28672
	v_exp_f32_e32 v218, v98
	v_exp_f32_e32 v222, v99
	v_cvt_pk_bf16_f32 v229, v183, v190
	s_waitcnt lgkmcnt(1)
	v_mfma_f32_32x32x16_bf16 v[32:47], v[204:207], v[232:235], v[32:47]
	s_add_i32 m0, m0, 0x4000
	ds_read_b128 v[96:99], v252 offset:16384
	global_load_lds_dwordx4 v144, s[100:101]
	v_exp_f32_e32 v211, v100
	v_exp_f32_e32 v215, v101
	v_cvt_pk_bf16_f32 v230, v184, v192
	s_waitcnt lgkmcnt(1)
	v_mfma_f32_32x32x16_bf16 v[16:31], v[240:243], v[232:235], v[16:31]
	ds_read_b128 v[224:227], v252 offset:20480
	v_exp_f32_e32 v209, v102
	v_exp_f32_e32 v213, v103
	v_cvt_pk_bf16_f32 v231, v185, v193
	s_waitcnt lgkmcnt(1)
	v_mfma_f32_32x32x16_bf16 v[64:79], v[96:99], v[236:239], v[64:79]
	s_add_i32 m0, m0, 0xffffc400
	ds_read_b128 v[100:103], v252 offset:24576
	global_load_lds_dwordx4 v142, s[98:99]
	v_exp_f32_e32 v210, v104
	v_exp_f32_e32 v214, v105
	v_cvt_pk_bf16_f32 v232, v188, v196
	s_waitcnt lgkmcnt(1)
	v_mfma_f32_32x32x16_bf16 v[48:63], v[224:227], v[236:239], v[48:63]
	ds_read_b128 v[96:99], v252 offset:28672
	v_exp_f32_e32 v207, v106
	v_exp_f32_e32 v208, v107
	v_cvt_pk_bf16_f32 v233, v191, v197
	s_waitcnt lgkmcnt(1)
	v_mfma_f32_32x32x16_bf16 v[32:47], v[100:103], v[236:239], v[32:47]
	s_add_i32 m0, m0, 0x4000
	ds_read_b128 v[104:107], v253 offset:16384
	global_load_lds_dwordx4 v146, s[100:101]
	s_add_u32 s98, s98, 0x20000
	s_addc_u32 s99, s99, 0
	s_add_u32 s100, s100, 0x80
	s_addc_u32 s101, s101, 0
	v_exp_f32_e32 v205, v108
	v_exp_f32_e32 v206, v109
	v_cvt_pk_bf16_f32 v234, v189, v194
	s_waitcnt lgkmcnt(1)
	v_mfma_f32_32x32x16_bf16 v[16:31], v[96:99], v[236:239], v[16:31]
	ds_read_b128 v[100:103], v253 offset:20480
	v_exp_f32_e32 v204, v110
	v_exp_f32_e32 v203, v111
	v_cvt_pk_bf16_f32 v235, v186, v195
	s_waitcnt lgkmcnt(1)
	v_mfma_f32_32x32x16_bf16 v[64:79], v[104:107], v[228:231], v[64:79]
	ds_read_b128 v[96:99], v253 offset:24576
	v_exp_f32_e32 v130, v80
	v_exp_f32_e32 v187, v81
	s_waitcnt lgkmcnt(1)
	v_mfma_f32_32x32x16_bf16 v[48:63], v[100:103], v[228:231], v[48:63]
	ds_read_b128 v[104:107], v253 offset:28672
	v_exp_f32_e32 v183, v82
	v_exp_f32_e32 v190, v83
	s_waitcnt lgkmcnt(1)
	v_mfma_f32_32x32x16_bf16 v[32:47], v[96:99], v[228:231], v[32:47]
	ds_read_b128 v[80:83], v254 offset:16384
	v_exp_f32_e32 v184, v84
	v_exp_f32_e32 v192, v85
	s_waitcnt lgkmcnt(1)
	v_mfma_f32_32x32x16_bf16 v[16:31], v[104:107], v[228:231], v[16:31]
	ds_read_b128 v[96:99], v254 offset:20480
	v_exp_f32_e32 v185, v86
	v_exp_f32_e32 v193, v87
	s_waitcnt lgkmcnt(1)
	v_mfma_f32_32x32x16_bf16 v[64:79], v[80:83], v[232:235], v[64:79]
	ds_read_b128 v[84:87], v254 offset:24576
	ds_read_b128 v[80:83], v198
	v_exp_f32_e32 v188, v88
	v_exp_f32_e32 v196, v89
	s_waitcnt lgkmcnt(2)
	v_mfma_f32_32x32x16_bf16 v[48:63], v[96:99], v[232:235], v[48:63]
	ds_read_b128 v[100:103], v254 offset:28672
	ds_read_b128 v[224:227], v198 offset:8192
	v_exp_f32_e32 v191, v90
	v_exp_f32_e32 v197, v91
	s_waitcnt lgkmcnt(3)
	v_mfma_f32_32x32x16_bf16 v[32:47], v[84:87], v[232:235], v[32:47]
	ds_read_b128 v[228:231], v200
	v_exp_f32_e32 v189, v92
	v_exp_f32_e32 v194, v93
	s_waitcnt lgkmcnt(2)
	v_mfma_f32_32x32x16_bf16 v[16:31], v[100:103], v[232:235], v[16:31]
	v_exp_f32_e32 v186, v94
	v_exp_f32_e32 v195, v95
	s_add_i32 s33, s33, 1
	s_cmpk_eq_i32 s33, 0x84
	s_cbranch_scc1 .Lattn_exit
; #define SB() __builtin_amdgcn_sched_barrier(0)
; __device__ __forceinline__ void attn_unit(unsigned char* ws, const float* sub_g, LAS unsigned char* lds, int h, int qb, float negM, float lam) {
;     ...
;         f32x16 s0, s1;
;         bf16x8 F0 = FLOAD(0), F1 = FLOAD(1), F2;
;         SB();
;         F2 = FLOAD(2); s0 = __builtin_amdgcn_mfma_f32_32x32x16_bf16(F0, qf[0], negm, 0, 0, 0); ADD4(pa, 0); pw[0][0] = cvtpk(pa[0], pa[1]); SB();
;         F0 = FLOAD(3); s1 = __builtin_amdgcn_mfma_f32_32x32x16_bf16(F1, qf[0], negm, 0, 0, 0); ADD4(pa, 4); pw[0][1] = cvtpk(pa[2], pa[3]); SB();
;         F1 = FLOAD(4); s0 = __builtin_amdgcn_mfma_f32_32x32x16_bf16(F2, qf[1], s0, 0, 0, 0); ADD4(pa, 8); pw[0][2] = cvtpk(pa[4], pa[5]); SB();
;         F2 = FLOAD(5); s1 = __builtin_amdgcn_mfma_f32_32x32x16_bf16(F0, qf[1], s1, 0, 0, 0); ADD4(pa, 12); pw[0][3] = cvtpk(pa[6], pa[7]); SB();
;         F0 = FLOAD(6); s0 = __builtin_amdgcn_mfma_f32_32x32x16_bf16(F1, qf[2], s0, 0, 0, 0); ADD4(pb, 0); pw[1][0] = cvtpk(pa[8], pa[9]); SB();
;         F1 = FLOAD(7); s1 = __builtin_amdgcn_mfma_f32_32x32x16_bf16(F2, qf[2], s1, 0, 0, 0); ADD4(pb, 4); pw[1][1] = cvtpk(pa[10], pa[11]); SB();
;         F2 = FLOAD(8); s0 = __builtin_amdgcn_mfma_f32_32x32x16_bf16(F0, qf[3], s0, 0, 0, 0); ADD4(pb, 8); pw[1][2] = cvtpk(pa[12], pa[13]); SB();
;         F0 = FLOAD(9); s1 = __builtin_amdgcn_mfma_f32_32x32x16_bf16(F1, qf[3], s1, 0, 0, 0); ADD4(pb, 12); pw[1][3] = cvtpk(pa[14], pa[15]); SB();
;         F1 = FLOAD(10); o[0] = __builtin_amdgcn_mfma_f32_32x32x16_bf16(F2, __builtin_bit_cast(bf16x8, pw[0]), o[0], 0, 0, 0); pw[2][0] = cvtpk(pb[0], pb[1]); EXP2(s0, pa, 0); SB();
;         F2 = FLOAD(11); o[1] = __builtin_amdgcn_mfma_f32_32x32x16_bf16(F0, __builtin_bit_cast(bf16x8, pw[0]), o[1], 0, 0, 0); pw[2][1] = cvtpk(pb[2], pb[3]); EXP2(s0, pa, 2); SB();
;         F0 = FLOAD(12); o[2] = __builtin_amdgcn_mfma_f32_32x32x16_bf16(F1, __builtin_bit_cast(bf16x8, pw[0]), o[2], 0, 0, 0); pw[2][2] = cvtpk(pb[4], pb[5]); EXP2(s0, pa, 4); SB();
;         F1 = FLOAD(13); o[3] = __builtin_amdgcn_mfma_f32_32x32x16_bf16(F2, __builtin_bit_cast(bf16x8, pw[0]), o[3], 0, 0, 0); pw[2][3] = cvtpk(pb[6], pb[7]); EXP2(s0, pa, 6); SB();
;         F2 = FLOAD(14); o[0] = __builtin_amdgcn_mfma_f32_32x32x16_bf16(F0, __builtin_bit_cast(bf16x8, pw[1]), o[0], 0, 0, 0); pw[3][0] = cvtpk(pb[8], pb[9]); EXP2(s0, pa, 8); SB();
.Lattn_c0:
	v_add_f32_e32 v85, v216, v217
	v_add_f32_e32 v86, v199, v219
	s_waitcnt lgkmcnt(2)
	v_mfma_f32_32x32x16_bf16 v[96:111], v[80:83], v[112:115], v[0:15]
	v_add_f32_e32 v85, v85, v218
	v_add_f32_e32 v80, v86, v222
	v_cvt_pk_bf16_f32 v232, v217, v219
	ds_read_b128 v[236:239], v200 offset:8192
	v_add_f32_e32 v81, v85, v211
	v_add_f32_e32 v80, v80, v215
	v_cvt_pk_bf16_f32 v233, v218, v222
	v_add_f32_e32 v199, v81, v209
	v_add_f32_e32 v223, v80, v213
	s_waitcnt lgkmcnt(2)
	v_mfma_f32_32x32x16_bf16 v[80:95], v[224:227], v[112:115], v[0:15]
	ds_read_b128 v[216:219], v201
	v_add_f32_e32 v199, v199, v210
	v_add_f32_e32 v223, v223, v214
	s_waitcnt lgkmcnt(2)
	v_mfma_f32_32x32x16_bf16 v[96:111], v[228:231], v[116:119], v[96:111]
	v_add_f32_e32 v199, v199, v207
	v_add_f32_e32 v226, v223, v208
	v_cvt_pk_bf16_f32 v234, v211, v215
	ds_read_b128 v[222:225], v201 offset:8192
	v_add_f32_e32 v199, v199, v205
	v_add_f32_e32 v211, v226, v206
	v_cvt_pk_bf16_f32 v235, v209, v213
	v_add_f32_e32 v199, v199, v204
	v_add_f32_e32 v211, v211, v203
	s_waitcnt lgkmcnt(2)
	v_mfma_f32_32x32x16_bf16 v[80:95], v[236:239], v[116:119], v[80:95]
	ds_read_b128 v[226:229], v202
	v_add_f32_e32 v199, v199, v130
	v_add_f32_e32 v211, v211, v187
	s_waitcnt lgkmcnt(2)
	v_mfma_f32_32x32x16_bf16 v[96:111], v[216:219], v[120:123], v[96:111]
	v_add_f32_e32 v199, v199, v183
	v_add_f32_e32 v211, v211, v190
	v_cvt_pk_bf16_f32 v236, v210, v214
	ds_read_b128 v[240:243], v202 offset:8192
	v_add_f32_e32 v199, v199, v184
	v_add_f32_e32 v209, v211, v192
	v_cvt_pk_bf16_f32 v237, v207, v208
	v_add_f32_e32 v199, v199, v185
	v_add_f32_e32 v213, v209, v193
	s_waitcnt lgkmcnt(2)
	v_mfma_f32_32x32x16_bf16 v[80:95], v[222:225], v[120:123], v[80:95]
	ds_read_b128 v[208:211], v251 offset:49152
	v_add_f32_e32 v199, v199, v188
	v_add_f32_e32 v207, v213, v196
	s_waitcnt lgkmcnt(2)
	v_mfma_f32_32x32x16_bf16 v[96:111], v[226:229], v[124:127], v[96:111]
	v_add_f32_e32 v199, v199, v191
	v_add_f32_e32 v207, v207, v197
	v_cvt_pk_bf16_f32 v238, v205, v206
	ds_read_b128 v[224:227], v251 offset:53248
	v_add_f32_e32 v199, v199, v189
	v_add_f32_e32 v205, v207, v194
	v_cvt_pk_bf16_f32 v239, v204, v203
	v_add_f32_e32 v216, v199, v186
	v_add_f32_e32 v199, v205, v195
	s_waitcnt lgkmcnt(2)
	v_mfma_f32_32x32x16_bf16 v[80:95], v[240:243], v[124:127], v[80:95]
	s_waitcnt vmcnt(0)
	s_barrier
	s_waitcnt lgkmcnt(1)
	v_mfma_f32_32x32x16_bf16 v[64:79], v[208:211], v[232:235], v[64:79]
	s_add_i32 m0, s8, 0x10000
	ds_read_b128 v[204:207], v251 offset:57344
	global_load_lds_dwordx4 v140, s[98:99]
	v_exp_f32_e32 v217, v96
	v_exp_f32_e32 v219, v97
	v_cvt_pk_bf16_f32 v228, v130, v187
	s_waitcnt lgkmcnt(1)
	v_mfma_f32_32x32x16_bf16 v[48:63], v[224:227], v[232:235], v[48:63]
	ds_read_b128 v[240:243], v251 offset:61440
	v_exp_f32_e32 v218, v98
	v_exp_f32_e32 v222, v99
	v_cvt_pk_bf16_f32 v229, v183, v190
	s_waitcnt lgkmcnt(1)
	v_mfma_f32_32x32x16_bf16 v[32:47], v[204:207], v[232:235], v[32:47]
	s_add_i32 m0, m0, 0x4000
	ds_read_b128 v[96:99], v252 offset:49152
	global_load_lds_dwordx4 v144, s[100:101]
	v_exp_f32_e32 v211, v100
	v_exp_f32_e32 v215, v101
	v_cvt_pk_bf16_f32 v230, v184, v192
	s_waitcnt lgkmcnt(1)
	v_mfma_f32_32x32x16_bf16 v[16:31], v[240:243], v[232:235], v[16:31]
	ds_read_b128 v[224:227], v252 offset:53248
	v_exp_f32_e32 v209, v102
	v_exp_f32_e32 v213, v103
	v_cvt_pk_bf16_f32 v231, v185, v193
	s_waitcnt lgkmcnt(1)
	v_mfma_f32_32x32x16_bf16 v[64:79], v[96:99], v[236:239], v[64:79]
	s_add_i32 m0, m0, 0xffffc400
	ds_read_b128 v[100:103], v252 offset:57344
	global_load_lds_dwordx4 v142, s[98:99]
	v_exp_f32_e32 v210, v104
	v_exp_f32_e32 v214, v105
	v_cvt_pk_bf16_f32 v232, v188, v196
	s_waitcnt lgkmcnt(1)
	v_mfma_f32_32x32x16_bf16 v[48:63], v[224:227], v[236:239], v[48:63]
	ds_read_b128 v[96:99], v252 offset:61440
	v_exp_f32_e32 v207, v106
	v_exp_f32_e32 v208, v107
	v_cvt_pk_bf16_f32 v233, v191, v197
	s_waitcnt lgkmcnt(1)
	v_mfma_f32_32x32x16_bf16 v[32:47], v[100:103], v[236:239], v[32:47]
	s_add_i32 m0, m0, 0x4000
	ds_read_b128 v[104:107], v253 offset:49152
	global_load_lds_dwordx4 v146, s[100:101]
	s_add_u32 s98, s98, 0x20000
	s_addc_u32 s99, s99, 0
	s_add_u32 s100, s100, 0x80
	s_addc_u32 s101, s101, 0
	v_exp_f32_e32 v205, v108
	v_exp_f32_e32 v206, v109
	v_cvt_pk_bf16_f32 v234, v189, v194
	s_waitcnt lgkmcnt(1)
	v_mfma_f32_32x32x16_bf16 v[16:31], v[96:99], v[236:239], v[16:31]
	ds_read_b128 v[100:103], v253 offset:53248
	v_exp_f32_e32 v204, v110
	v_exp_f32_e32 v203, v111
	v_cvt_pk_bf16_f32 v235, v186, v195
	s_waitcnt lgkmcnt(1)
	v_mfma_f32_32x32x16_bf16 v[64:79], v[104:107], v[228:231], v[64:79]
	ds_read_b128 v[96:99], v253 offset:57344
	v_exp_f32_e32 v130, v80
	v_exp_f32_e32 v187, v81
	s_waitcnt lgkmcnt(1)
	v_mfma_f32_32x32x16_bf16 v[48:63], v[100:103], v[228:231], v[48:63]
	ds_read_b128 v[104:107], v253 offset:61440
	v_exp_f32_e32 v183, v82
	v_exp_f32_e32 v190, v83
	s_waitcnt lgkmcnt(1)
	v_mfma_f32_32x32x16_bf16 v[32:47], v[96:99], v[228:231], v[32:47]
	ds_read_b128 v[80:83], v254 offset:49152
	v_exp_f32_e32 v184, v84
	v_exp_f32_e32 v192, v85
	s_waitcnt lgkmcnt(1)
	v_mfma_f32_32x32x16_bf16 v[16:31], v[104:107], v[228:231], v[16:31]
	ds_read_b128 v[96:99], v254 offset:53248
	v_exp_f32_e32 v185, v86
	v_exp_f32_e32 v193, v87
	s_waitcnt lgkmcnt(1)
	v_mfma_f32_32x32x16_bf16 v[64:79], v[80:83], v[232:235], v[64:79]
	ds_read_b128 v[84:87], v254 offset:57344
	ds_read_b128 v[80:83], v198 offset:32768
	v_exp_f32_e32 v188, v88
	v_exp_f32_e32 v196, v89
	s_waitcnt lgkmcnt(2)
	v_mfma_f32_32x32x16_bf16 v[48:63], v[96:99], v[232:235], v[48:63]
	ds_read_b128 v[100:103], v254 offset:61440
	ds_read_b128 v[224:227], v198 offset:40960
	v_exp_f32_e32 v191, v90
	v_exp_f32_e32 v197, v91
	s_waitcnt lgkmcnt(3)
	v_mfma_f32_32x32x16_bf16 v[32:47], v[84:87], v[232:235], v[32:47]
	ds_read_b128 v[228:231], v200 offset:32768
	v_exp_f32_e32 v189, v92
	v_exp_f32_e32 v194, v93
	s_waitcnt lgkmcnt(2)
	v_mfma_f32_32x32x16_bf16 v[16:31], v[100:103], v[232:235], v[16:31]
	v_exp_f32_e32 v186, v94
	v_exp_f32_e32 v195, v95
	s_add_i32 s33, s33, 1
	s_branch .Lattn_c1
